# P1: ssq rows and (gate tiles) the gate-bias quad fetched at the top of each tile into registers the K-loop never touches; bias parked in a per-wave LDS slot; epilogue issues no global loads / no vmcnt
# baseline (speedup 1.0000x reference)
;     __device__ __forceinline__ void operator()(AccT& acc, const Unit& u, int wr, int wc, int fr, int fq) const {
;         const bool gate = u.pn >= 5;
;         const int col0 = u.pn * 256 + wc * 32 + 8 * fq;
;         f32x4 gb[2][2];
; #pragma unroll
;         for (int bj = 0; bj < 2; ++bj)
; #pragma unroll
;             for (int n = 0; n < 2; ++n) gb[bj][n] = gate ? *(const f32x4*)(gbias + (col0 - 1280) + bj * 128 + 4 * n) : (f32x4){0.f, 0.f, 0.f, 0.f};
;         float rsv[2][4];
; #pragma unroll
;         for (int ai = 0; ai < 2; ++ai)
; #pragma unroll
;             for (int m = 0; m < 4; ++m) rsv[ai][m] = ssq[u.pm * 256 + ai * 128 + wr * 64 + m * 16 + fr];
.LBB0_171:
	s_lshl_b32 s13, s49, 8
	s_add_i32 s13, s13, s33
	v_add_u32_e32 v254, s13, v162
	v_mov_b32_e32 v255, 0
	v_lshl_add_u64 v[254:255], v[254:255], 2, s[46:47]
	global_load_dword v238, v[254:255], off
	global_load_dword v239, v[254:255], off offset:64
	global_load_dword v240, v[254:255], off offset:128
	global_load_dword v241, v[254:255], off offset:192
	global_load_dword v242, v[254:255], off offset:512
	global_load_dword v243, v[254:255], off offset:576
	global_load_dword v244, v[254:255], off offset:640
	global_load_dword v245, v[254:255], off offset:704
	s_cmp_lt_i32 s50, 5
	s_cbranch_scc1 .Lmy_p1top_skip
	s_lshl_b32 s13, s50, 8
	s_or_b32 s13, s13, s37
	v_lshl_add_u32 v254, v163, 3, s13
	v_bfe_u32 v255, v162, 1, 1
	v_lshl_add_u32 v254, v255, 7, v254
	v_and_b32_e32 v255, 1, v162
	v_lshl_add_u32 v254, v255, 2, v254
	v_mov_b32_e32 v255, 0
	v_lshl_add_u64 v[254:255], v[254:255], 2, s[2:3]
	s_mov_b32 s16, 0xffffec00
	s_mov_b32 s17, -1
	v_lshl_add_u64 v[254:255], v[254:255], 0, s[16:17]
	global_load_dwordx4 v[250:253], v[254:255], off

; __device__ __forceinline__ u32x4 pack8(const float* f) { u32x4 w; w.x = cvt_pk_bf16(f[0], f[1]); w.y = cvt_pk_bf16(f[2], f[3]); w.z = cvt_pk_bf16(f[4], f[5]); w.w = cvt_pk_bf16(f[6], f[7]); return w; }
;     __device__ __forceinline__ void operator()(AccT& acc, const Unit& u, int wr, int wc, int fr, int fq) const {
;         const bool gate = u.pn >= 5;
;         const int col0 = u.pn * 256 + wc * 32 + 8 * fq;
;         f32x4 gb[2][2];
; #pragma unroll
;         for (int bj = 0; bj < 2; ++bj)
; #pragma unroll
;             for (int n = 0; n < 2; ++n) gb[bj][n] = gate ? *(const f32x4*)(gbias + (col0 - 1280) + bj * 128 + 4 * n) : (f32x4){0.f, 0.f, 0.f, 0.f};
;         float rsv[2][4];
; #pragma unroll
;         for (int ai = 0; ai < 2; ++ai)
; #pragma unroll
;             for (int m = 0; m < 4; ++m) rsv[ai][m] = ssq[u.pm * 256 + ai * 128 + wr * 64 + m * 16 + fr];
; #pragma unroll
;         for (int ai = 0; ai < 2; ++ai)
; #pragma unroll
;             for (int m = 0; m < 4; ++m) {
;                 const int row = u.pm * 256 + ai * 128 + wr * 64 + m * 16 + fr;
;                 const float rs = __builtin_amdgcn_rsqf(rsv[ai][m] * (1.0f / 1024.0f) + EPS);
;                 bf16_t* rowp = P + (size_t)row * INW + col0;
; #pragma unroll
;                 for (int bj = 0; bj < 2; ++bj) {
;                     float v[8];
; #pragma unroll
;                     for (int n = 0; n < 2; ++n)
; #pragma unroll
;                         for (int j = 0; j < 4; ++j) {
;                             float x = acc[ai][bj][m][n][j] * rs;
;                             if (gate) { x += gb[bj][n][j]; x = __builtin_amdgcn_rcpf(1.0f + __builtin_amdgcn_exp2f(-LOG2E * x)); }
;                             v[n * 4 + j] = x;
;                         }
;                     *(u32x4*)(rowp + bj * 128) = pack8(v);
;                 }
.LBB0_177:
	s_cmp_gt_i32 s50, 4
	s_cselect_b64 s[42:43], -1, 0
	s_lshl_b32 s0, s50, 8
	v_mov_b32_e32 v160, v162
	s_or_b32 s0, s0, s37
	v_lshl_add_u32 v158, v163, 3, s0
	v_ashrrev_i32_e32 v159, 31, v158
	v_mov_b32_e32 v52, 0
	v_mov_b32_e32 v53, 0
	v_mov_b32_e32 v54, 0
	v_mov_b32_e32 v55, 0
	v_mov_b32_e32 v44, 0
	v_mov_b32_e32 v45, 0
	v_mov_b32_e32 v46, 0
	v_mov_b32_e32 v47, 0
	v_mov_b32_e32 v40, 0
	v_mov_b32_e32 v41, 0
	v_mov_b32_e32 v42, 0
	v_mov_b32_e32 v43, 0
	v_mov_b32_e32 v32, 0
	v_mov_b32_e32 v33, 0
	v_mov_b32_e32 v34, 0
	v_mov_b32_e32 v35, 0
	s_cmp_lt_i32 s50, 5
	s_cbranch_scc1 .Lmy_p1_nobias
	s_lshl_b32 s0, s33, 4
	s_lshl_b32 s1, s37, 3
	s_add_i32 s0, s0, s1
	s_add_i32 s0, s0, 0x20000
	v_lshl_add_u32 v156, v163, 6, s0
	v_and_b32_e32 v157, 3, v162
	v_lshl_add_u32 v157, v157, 4, v156
	ds_write_b128 v157, v[250:253]
	ds_read_b128 v[52:55], v156
	ds_read_b128 v[44:47], v156 offset:16
	ds_read_b128 v[40:43], v156 offset:32
	ds_read_b128 v[32:35], v156 offset:48
.Lmy_p1_nobias:
	s_lshl_b32 s0, s49, 8
	s_add_i32 s0, s0, s33
	v_add_u32_e32 v160, s0, v160
	v_mov_b32_e32 v161, v238
	v_mov_b32_e32 v179, v239
	v_mov_b32_e32 v177, v240
	v_mov_b32_e32 v175, v241
	v_mov_b32_e32 v173, v242
	v_mov_b32_e32 v171, v243
	v_mov_b32_e32 v169, v244
	v_mov_b32_e32 v167, v245
	v_add_u32_e32 v178, 16, v160
	v_add_u32_e32 v176, 32, v160
	v_add_u32_e32 v174, 48, v160
	v_add_u32_e32 v172, 0x80, v160
	v_add_u32_e32 v170, 0x90, v160
	v_add_u32_e32 v168, 0xa0, v160
	v_add_u32_e32 v166, 0xb0, v160
	v_lshlrev_b64 v[158:159], 1, v[158:159]
	s_andn2_b64 vcc, exec, s[40:41]
	s_waitcnt lgkmcnt(0)
	s_cmp_eq_u64 s[42:43], 0
	s_cbranch_scc1 .Lmy_p1_nongate
	v_mul_f32_e32 v214, 0xbfb8aa3b, v52
	v_mul_f32_e32 v215, 0xbfb8aa3b, v53
	v_mul_f32_e32 v216, 0xbfb8aa3b, v54
	v_mul_f32_e32 v217, 0xbfb8aa3b, v55
	v_mul_f32_e32 v218, 0xbfb8aa3b, v44
	v_mul_f32_e32 v219, 0xbfb8aa3b, v45
	v_mul_f32_e32 v220, 0xbfb8aa3b, v46
	v_mul_f32_e32 v221, 0xbfb8aa3b, v47
	v_mul_f32_e32 v234, 0xbfb8aa3b, v40
	v_mul_f32_e32 v235, 0xbfb8aa3b, v41
	v_mul_f32_e32 v236, 0xbfb8aa3b, v42
	v_mul_f32_e32 v237, 0xbfb8aa3b, v43
	v_mul_f32_e32 v250, 0xbfb8aa3b, v32
	v_mul_f32_e32 v251, 0xbfb8aa3b, v33
	v_mul_f32_e32 v252, 0xbfb8aa3b, v34
	v_mul_f32_e32 v253, 0xbfb8aa3b, v35
	v_fmamk_f32 v156, v161, 0x3a800000, v223
	v_rsq_f32_e32 v180, v156
	s_nop 0
	v_mul_f32_e32 v180, 0xbfb8aa3b, v180
	v_mov_b64_e32 v[156:157], s[84:85]
	v_mad_i64_i32 v[160:161], s[0:1], v160, s89, v[156:157]
	v_lshl_add_u64 v[160:161], v[160:161], 0, v[158:159]
	v_fma_f32 v206, v142, v180, v214
	v_fma_f32 v207, v143, v180, v215
	v_fma_f32 v208, v144, v180, v216
	v_fma_f32 v209, v145, v180, v217
	v_fma_f32 v210, v138, v180, v218
	v_fma_f32 v211, v139, v180, v219
	v_fma_f32 v212, v140, v180, v220
	v_fma_f32 v213, v141, v180, v221
	v_exp_f32_e32 v206, v206
	v_exp_f32_e32 v207, v207
	v_exp_f32_e32 v208, v208
	v_exp_f32_e32 v209, v209
	v_exp_f32_e32 v210, v210
	v_exp_f32_e32 v211, v211
	v_exp_f32_e32 v212, v212
	v_exp_f32_e32 v213, v213
	v_add_f32_e32 v206, 1.0, v206
	v_add_f32_e32 v207, 1.0, v207
	v_add_f32_e32 v208, 1.0, v208
	v_add_f32_e32 v209, 1.0, v209
	v_add_f32_e32 v210, 1.0, v210
	v_add_f32_e32 v211, 1.0, v211
	v_add_f32_e32 v212, 1.0, v212
	v_add_f32_e32 v213, 1.0, v213
	v_rcp_f32_e32 v142, v206
	v_rcp_f32_e32 v143, v207
	v_rcp_f32_e32 v144, v208
	v_rcp_f32_e32 v145, v209
	v_rcp_f32_e32 v181, v210
	v_rcp_f32_e32 v182, v211
	v_rcp_f32_e32 v183, v212
	v_rcp_f32_e32 v141, v213
	v_cvt_pk_bf16_f32 v138, v142, v143
	v_cvt_pk_bf16_f32 v139, v144, v145
	v_cvt_pk_bf16_f32 v140, v181, v182
	v_cvt_pk_bf16_f32 v141, v183, v141
	global_store_dwordx4 v[160:161], v[138:141], off
	s_nop 1
	v_fma_f32 v206, v134, v180, v234
	v_fma_f32 v207, v135, v180, v235
	v_fma_f32 v208, v136, v180, v236
	v_fma_f32 v209, v137, v180, v237
	v_fma_f32 v210, v130, v180, v250
	v_fma_f32 v211, v131, v180, v251
	v_fma_f32 v212, v132, v180, v252
	v_fma_f32 v213, v133, v180, v253
	v_exp_f32_e32 v206, v206
	v_exp_f32_e32 v207, v207
	v_exp_f32_e32 v208, v208
	v_exp_f32_e32 v209, v209
	v_exp_f32_e32 v210, v210
	v_exp_f32_e32 v211, v211
	v_exp_f32_e32 v212, v212
	v_exp_f32_e32 v213, v213
	v_add_f32_e32 v206, 1.0, v206
	v_add_f32_e32 v207, 1.0, v207
	v_add_f32_e32 v208, 1.0, v208
	v_add_f32_e32 v209, 1.0, v209
	v_add_f32_e32 v210, 1.0, v210
	v_add_f32_e32 v211, 1.0, v211
	v_add_f32_e32 v212, 1.0, v212
	v_add_f32_e32 v213, 1.0, v213
	v_rcp_f32_e32 v134, v206
	v_rcp_f32_e32 v135, v207
	v_rcp_f32_e32 v136, v208
	v_rcp_f32_e32 v137, v209
	v_rcp_f32_e32 v138, v210
	v_rcp_f32_e32 v139, v211
	v_rcp_f32_e32 v140, v212
	v_rcp_f32_e32 v133, v213
	v_cvt_pk_bf16_f32 v130, v134, v135
	v_cvt_pk_bf16_f32 v131, v136, v137
	v_cvt_pk_bf16_f32 v132, v138, v139
	v_cvt_pk_bf16_f32 v133, v140, v133
	global_store_dwordx4 v[160:161], v[130:133], off offset:256
	s_nop 1
	v_fmamk_f32 v130, v179, 0x3a800000, v223
	v_rsq_f32_e32 v132, v130
	s_nop 0
	v_mul_f32_e32 v132, 0xbfb8aa3b, v132
	v_mad_i64_i32 v[130:131], s[0:1], v178, s89, v[156:157]
	v_lshl_add_u64 v[130:131], v[130:131], 0, v[158:159]
	v_fma_f32 v206, v126, v132, v214
	v_fma_f32 v207, v127, v132, v215
	v_fma_f32 v208, v128, v132, v216
	v_fma_f32 v209, v129, v132, v217
	v_fma_f32 v210, v122, v132, v218
	v_fma_f32 v211, v123, v132, v219
	v_fma_f32 v212, v124, v132, v220
	v_fma_f32 v213, v125, v132, v221
	v_exp_f32_e32 v206, v206
	v_exp_f32_e32 v207, v207
	v_exp_f32_e32 v208, v208
	v_exp_f32_e32 v209, v209
	v_exp_f32_e32 v210, v210
	v_exp_f32_e32 v211, v211
	v_exp_f32_e32 v212, v212
	v_exp_f32_e32 v213, v213
	v_add_f32_e32 v206, 1.0, v206
	v_add_f32_e32 v207, 1.0, v207
	v_add_f32_e32 v208, 1.0, v208
	v_add_f32_e32 v209, 1.0, v209
	v_add_f32_e32 v210, 1.0, v210
; __device__ __forceinline__ u32x4 pack8(const float* f) { u32x4 w; w.x = cvt_pk_bf16(f[0], f[1]); w.y = cvt_pk_bf16(f[2], f[3]); w.z = cvt_pk_bf16(f[4], f[5]); w.w = cvt_pk_bf16(f[6], f[7]); return w; }
;     __device__ __forceinline__ void operator()(AccT& acc, const Unit& u, int wr, int wc, int fr, int fq) const {
;     ...
;         for (int ai = 0; ai < 2; ++ai)
; #pragma unroll
;             for (int m = 0; m < 4; ++m) {
;                 const int row = u.pm * 256 + ai * 128 + wr * 64 + m * 16 + fr;
;                 const float rs = __builtin_amdgcn_rsqf(rsv[ai][m] * (1.0f / 1024.0f) + EPS);
;                 bf16_t* rowp = P + (size_t)row * INW + col0;
; #pragma unroll
;                 for (int bj = 0; bj < 2; ++bj) {
;                     float v[8];
; #pragma unroll
;                     for (int n = 0; n < 2; ++n)
; #pragma unroll
;                         for (int j = 0; j < 4; ++j) {
;                             float x = acc[ai][bj][m][n][j] * rs;
;                             if (gate) { x += gb[bj][n][j]; x = __builtin_amdgcn_rcpf(1.0f + __builtin_amdgcn_exp2f(-LOG2E * x)); }
;                             v[n * 4 + j] = x;
;                         }
;                     *(u32x4*)(rowp + bj * 128) = pack8(v);
;                 }
	v_add_f32_e32 v211, 1.0, v211
	v_add_f32_e32 v212, 1.0, v212
	v_add_f32_e32 v213, 1.0, v213
	v_rcp_f32_e32 v126, v206
	v_rcp_f32_e32 v127, v207
	v_rcp_f32_e32 v128, v208
	v_rcp_f32_e32 v129, v209
	v_rcp_f32_e32 v133, v210
	v_rcp_f32_e32 v134, v211
	v_rcp_f32_e32 v135, v212
	v_rcp_f32_e32 v125, v213
	v_cvt_pk_bf16_f32 v122, v126, v127
	v_cvt_pk_bf16_f32 v123, v128, v129
	v_cvt_pk_bf16_f32 v124, v133, v134
	v_cvt_pk_bf16_f32 v125, v135, v125
	global_store_dwordx4 v[130:131], v[122:125], off
	s_nop 1
	v_fma_f32 v206, v118, v132, v234
	v_fma_f32 v207, v119, v132, v235
	v_fma_f32 v208, v120, v132, v236
	v_fma_f32 v209, v121, v132, v237
	v_fma_f32 v210, v114, v132, v250
	v_fma_f32 v211, v115, v132, v251
	v_fma_f32 v212, v116, v132, v252
	v_fma_f32 v213, v117, v132, v253
	v_exp_f32_e32 v206, v206
	v_exp_f32_e32 v207, v207
	v_exp_f32_e32 v208, v208
	v_exp_f32_e32 v209, v209
	v_exp_f32_e32 v210, v210
	v_exp_f32_e32 v211, v211
	v_exp_f32_e32 v212, v212
	v_exp_f32_e32 v213, v213
	v_add_f32_e32 v206, 1.0, v206
	v_add_f32_e32 v207, 1.0, v207
	v_add_f32_e32 v208, 1.0, v208
	v_add_f32_e32 v209, 1.0, v209
	v_add_f32_e32 v210, 1.0, v210
	v_add_f32_e32 v211, 1.0, v211
	v_add_f32_e32 v212, 1.0, v212
	v_add_f32_e32 v213, 1.0, v213
	v_rcp_f32_e32 v118, v206
	v_rcp_f32_e32 v119, v207
	v_rcp_f32_e32 v120, v208
	v_rcp_f32_e32 v121, v209
	v_rcp_f32_e32 v122, v210
	v_rcp_f32_e32 v123, v211
	v_rcp_f32_e32 v124, v212
	v_rcp_f32_e32 v117, v213
	v_cvt_pk_bf16_f32 v114, v118, v119
	v_cvt_pk_bf16_f32 v115, v120, v121
	v_cvt_pk_bf16_f32 v116, v122, v123
	v_cvt_pk_bf16_f32 v117, v124, v117
	global_store_dwordx4 v[130:131], v[114:117], off offset:256
	s_nop 1
	v_fmamk_f32 v114, v177, 0x3a800000, v223
	v_rsq_f32_e32 v116, v114
	s_nop 0
	v_mul_f32_e32 v116, 0xbfb8aa3b, v116
	v_mad_i64_i32 v[114:115], s[0:1], v176, s89, v[156:157]
	v_lshl_add_u64 v[114:115], v[114:115], 0, v[158:159]
	v_fma_f32 v206, v110, v116, v214
	v_fma_f32 v207, v111, v116, v215
	v_fma_f32 v208, v112, v116, v216
	v_fma_f32 v209, v113, v116, v217
	v_fma_f32 v210, v106, v116, v218
	v_fma_f32 v211, v107, v116, v219
	v_fma_f32 v212, v108, v116, v220
	v_fma_f32 v213, v109, v116, v221
	v_exp_f32_e32 v206, v206
	v_exp_f32_e32 v207, v207
	v_exp_f32_e32 v208, v208
	v_exp_f32_e32 v209, v209
	v_exp_f32_e32 v210, v210
	v_exp_f32_e32 v211, v211
	v_exp_f32_e32 v212, v212
	v_exp_f32_e32 v213, v213
	v_add_f32_e32 v206, 1.0, v206
	v_add_f32_e32 v207, 1.0, v207
	v_add_f32_e32 v208, 1.0, v208
	v_add_f32_e32 v209, 1.0, v209
	v_add_f32_e32 v210, 1.0, v210
	v_add_f32_e32 v211, 1.0, v211
	v_add_f32_e32 v212, 1.0, v212
	v_add_f32_e32 v213, 1.0, v213
	v_rcp_f32_e32 v110, v206
	v_rcp_f32_e32 v111, v207
	v_rcp_f32_e32 v112, v208
	v_rcp_f32_e32 v113, v209
	v_rcp_f32_e32 v117, v210
	v_rcp_f32_e32 v118, v211
	v_rcp_f32_e32 v119, v212
	v_rcp_f32_e32 v109, v213
	v_cvt_pk_bf16_f32 v106, v110, v111
	v_cvt_pk_bf16_f32 v107, v112, v113
	v_cvt_pk_bf16_f32 v108, v117, v118
	v_cvt_pk_bf16_f32 v109, v119, v109
	global_store_dwordx4 v[114:115], v[106:109], off
	s_nop 1
	v_fma_f32 v206, v102, v116, v234
	v_fma_f32 v207, v103, v116, v235
	v_fma_f32 v208, v104, v116, v236
	v_fma_f32 v209, v105, v116, v237
	v_fma_f32 v210, v98, v116, v250
	v_fma_f32 v211, v99, v116, v251
	v_fma_f32 v212, v100, v116, v252
	v_fma_f32 v213, v101, v116, v253
	v_exp_f32_e32 v206, v206
	v_exp_f32_e32 v207, v207
	v_exp_f32_e32 v208, v208
	v_exp_f32_e32 v209, v209
	v_exp_f32_e32 v210, v210
	v_exp_f32_e32 v211, v211
	v_exp_f32_e32 v212, v212
	v_exp_f32_e32 v213, v213
	v_add_f32_e32 v206, 1.0, v206
	v_add_f32_e32 v207, 1.0, v207
	v_add_f32_e32 v208, 1.0, v208
	v_add_f32_e32 v209, 1.0, v209
	v_add_f32_e32 v210, 1.0, v210
	v_add_f32_e32 v211, 1.0, v211
	v_add_f32_e32 v212, 1.0, v212
	v_add_f32_e32 v213, 1.0, v213
	v_rcp_f32_e32 v102, v206
	v_rcp_f32_e32 v103, v207
	v_rcp_f32_e32 v104, v208
	v_rcp_f32_e32 v105, v209
	v_rcp_f32_e32 v106, v210
	v_rcp_f32_e32 v107, v211
	v_rcp_f32_e32 v108, v212
	v_rcp_f32_e32 v101, v213
	v_cvt_pk_bf16_f32 v98, v102, v103
	v_cvt_pk_bf16_f32 v99, v104, v105
	v_cvt_pk_bf16_f32 v100, v106, v107
	v_cvt_pk_bf16_f32 v101, v108, v101
	global_store_dwordx4 v[114:115], v[98:101], off offset:256
	s_nop 1
	v_fmamk_f32 v98, v175, 0x3a800000, v223
	v_rsq_f32_e32 v100, v98
	s_nop 0
	v_mul_f32_e32 v100, 0xbfb8aa3b, v100
	v_mad_i64_i32 v[98:99], s[0:1], v174, s89, v[156:157]
	v_lshl_add_u64 v[98:99], v[98:99], 0, v[158:159]
	v_fma_f32 v206, v92, v100, v214
	v_fma_f32 v207, v93, v100, v215
	v_fma_f32 v208, v94, v100, v216
	v_fma_f32 v209, v95, v100, v217
	v_fma_f32 v210, v88, v100, v218
	v_fma_f32 v211, v89, v100, v219
	v_fma_f32 v212, v90, v100, v220
	v_fma_f32 v213, v91, v100, v221
	v_exp_f32_e32 v206, v206
	v_exp_f32_e32 v207, v207
	v_exp_f32_e32 v208, v208
	v_exp_f32_e32 v209, v209
	v_exp_f32_e32 v210, v210
	v_exp_f32_e32 v211, v211
	v_exp_f32_e32 v212, v212
	v_exp_f32_e32 v213, v213
	v_add_f32_e32 v206, 1.0, v206
	v_add_f32_e32 v207, 1.0, v207
	v_add_f32_e32 v208, 1.0, v208
	v_add_f32_e32 v209, 1.0, v209
	v_add_f32_e32 v210, 1.0, v210
	v_add_f32_e32 v211, 1.0, v211
	v_add_f32_e32 v212, 1.0, v212
	v_add_f32_e32 v213, 1.0, v213
	v_rcp_f32_e32 v92, v206
	v_rcp_f32_e32 v93, v207
	v_rcp_f32_e32 v94, v208
	v_rcp_f32_e32 v95, v209
	v_rcp_f32_e32 v101, v210
	v_rcp_f32_e32 v102, v211
	v_rcp_f32_e32 v103, v212
	v_rcp_f32_e32 v91, v213
	v_cvt_pk_bf16_f32 v88, v92, v93
	v_cvt_pk_bf16_f32 v89, v94, v95
	v_cvt_pk_bf16_f32 v90, v101, v102
	v_cvt_pk_bf16_f32 v91, v103, v91
	global_store_dwordx4 v[98:99], v[88:91], off
	s_nop 1
	v_fma_f32 v206, v84, v100, v234
	v_fma_f32 v207, v85, v100, v235
	v_fma_f32 v208, v86, v100, v236
	v_fma_f32 v209, v87, v100, v237
; __device__ __forceinline__ u32x4 pack8(const float* f) { u32x4 w; w.x = cvt_pk_bf16(f[0], f[1]); w.y = cvt_pk_bf16(f[2], f[3]); w.z = cvt_pk_bf16(f[4], f[5]); w.w = cvt_pk_bf16(f[6], f[7]); return w; }
;     __device__ __forceinline__ void operator()(AccT& acc, const Unit& u, int wr, int wc, int fr, int fq) const {
;     ...
;         for (int ai = 0; ai < 2; ++ai)
; #pragma unroll
;             for (int m = 0; m < 4; ++m) {
;                 const int row = u.pm * 256 + ai * 128 + wr * 64 + m * 16 + fr;
;                 const float rs = __builtin_amdgcn_rsqf(rsv[ai][m] * (1.0f / 1024.0f) + EPS);
;                 bf16_t* rowp = P + (size_t)row * INW + col0;
; #pragma unroll
;                 for (int bj = 0; bj < 2; ++bj) {
;                     float v[8];
; #pragma unroll
;                     for (int n = 0; n < 2; ++n)
; #pragma unroll
;                         for (int j = 0; j < 4; ++j) {
;                             float x = acc[ai][bj][m][n][j] * rs;
;                             if (gate) { x += gb[bj][n][j]; x = __builtin_amdgcn_rcpf(1.0f + __builtin_amdgcn_exp2f(-LOG2E * x)); }
;                             v[n * 4 + j] = x;
;                         }
;                     *(u32x4*)(rowp + bj * 128) = pack8(v);
;                 }
	v_fma_f32 v210, v80, v100, v250
	v_fma_f32 v211, v81, v100, v251
	v_fma_f32 v212, v82, v100, v252
	v_fma_f32 v213, v83, v100, v253
	v_exp_f32_e32 v206, v206
	v_exp_f32_e32 v207, v207
	v_exp_f32_e32 v208, v208
	v_exp_f32_e32 v209, v209
	v_exp_f32_e32 v210, v210
	v_exp_f32_e32 v211, v211
	v_exp_f32_e32 v212, v212
	v_exp_f32_e32 v213, v213
	v_add_f32_e32 v206, 1.0, v206
	v_add_f32_e32 v207, 1.0, v207
	v_add_f32_e32 v208, 1.0, v208
	v_add_f32_e32 v209, 1.0, v209
	v_add_f32_e32 v210, 1.0, v210
	v_add_f32_e32 v211, 1.0, v211
	v_add_f32_e32 v212, 1.0, v212
	v_add_f32_e32 v213, 1.0, v213
	v_rcp_f32_e32 v84, v206
	v_rcp_f32_e32 v85, v207
	v_rcp_f32_e32 v86, v208
	v_rcp_f32_e32 v87, v209
	v_rcp_f32_e32 v88, v210
	v_rcp_f32_e32 v89, v211
	v_rcp_f32_e32 v90, v212
	v_rcp_f32_e32 v83, v213
	v_cvt_pk_bf16_f32 v80, v84, v85
	v_cvt_pk_bf16_f32 v81, v86, v87
	v_cvt_pk_bf16_f32 v82, v88, v89
	v_cvt_pk_bf16_f32 v83, v90, v83
	global_store_dwordx4 v[98:99], v[80:83], off offset:256
	s_nop 1
	v_fmamk_f32 v80, v173, 0x3a800000, v223
	v_rsq_f32_e32 v82, v80
	s_nop 0
	v_mul_f32_e32 v82, 0xbfb8aa3b, v82
	v_mad_i64_i32 v[80:81], s[0:1], v172, s89, v[156:157]
	v_lshl_add_u64 v[80:81], v[80:81], 0, v[158:159]
	v_fma_f32 v206, v76, v82, v214
	v_fma_f32 v207, v77, v82, v215
	v_fma_f32 v208, v78, v82, v216
	v_fma_f32 v209, v79, v82, v217
	v_fma_f32 v210, v72, v82, v218
	v_fma_f32 v211, v73, v82, v219
	v_fma_f32 v212, v74, v82, v220
	v_fma_f32 v213, v75, v82, v221
	v_exp_f32_e32 v206, v206
	v_exp_f32_e32 v207, v207
	v_exp_f32_e32 v208, v208
	v_exp_f32_e32 v209, v209
	v_exp_f32_e32 v210, v210
	v_exp_f32_e32 v211, v211
	v_exp_f32_e32 v212, v212
	v_exp_f32_e32 v213, v213
	v_add_f32_e32 v206, 1.0, v206
	v_add_f32_e32 v207, 1.0, v207
	v_add_f32_e32 v208, 1.0, v208
	v_add_f32_e32 v209, 1.0, v209
	v_add_f32_e32 v210, 1.0, v210
	v_add_f32_e32 v211, 1.0, v211
	v_add_f32_e32 v212, 1.0, v212
	v_add_f32_e32 v213, 1.0, v213
	v_rcp_f32_e32 v76, v206
	v_rcp_f32_e32 v77, v207
	v_rcp_f32_e32 v78, v208
	v_rcp_f32_e32 v79, v209
	v_rcp_f32_e32 v83, v210
	v_rcp_f32_e32 v84, v211
	v_rcp_f32_e32 v85, v212
	v_rcp_f32_e32 v75, v213
	v_cvt_pk_bf16_f32 v72, v76, v77
	v_cvt_pk_bf16_f32 v73, v78, v79
	v_cvt_pk_bf16_f32 v74, v83, v84
	v_cvt_pk_bf16_f32 v75, v85, v75
	global_store_dwordx4 v[80:81], v[72:75], off
	s_nop 1
	v_fma_f32 v206, v68, v82, v234
	v_fma_f32 v207, v69, v82, v235
	v_fma_f32 v208, v70, v82, v236
	v_fma_f32 v209, v71, v82, v237
	v_fma_f32 v210, v64, v82, v250
	v_fma_f32 v211, v65, v82, v251
	v_fma_f32 v212, v66, v82, v252
	v_fma_f32 v213, v67, v82, v253
	v_exp_f32_e32 v206, v206
	v_exp_f32_e32 v207, v207
	v_exp_f32_e32 v208, v208
	v_exp_f32_e32 v209, v209
	v_exp_f32_e32 v210, v210
	v_exp_f32_e32 v211, v211
	v_exp_f32_e32 v212, v212
	v_exp_f32_e32 v213, v213
	v_add_f32_e32 v206, 1.0, v206
	v_add_f32_e32 v207, 1.0, v207
	v_add_f32_e32 v208, 1.0, v208
	v_add_f32_e32 v209, 1.0, v209
	v_add_f32_e32 v210, 1.0, v210
	v_add_f32_e32 v211, 1.0, v211
	v_add_f32_e32 v212, 1.0, v212
	v_add_f32_e32 v213, 1.0, v213
	v_rcp_f32_e32 v68, v206
	v_rcp_f32_e32 v69, v207
	v_rcp_f32_e32 v70, v208
	v_rcp_f32_e32 v71, v209
	v_rcp_f32_e32 v72, v210
	v_rcp_f32_e32 v73, v211
	v_rcp_f32_e32 v74, v212
	v_rcp_f32_e32 v67, v213
	v_cvt_pk_bf16_f32 v64, v68, v69
	v_cvt_pk_bf16_f32 v65, v70, v71
	v_cvt_pk_bf16_f32 v66, v72, v73
	v_cvt_pk_bf16_f32 v67, v74, v67
	global_store_dwordx4 v[80:81], v[64:67], off offset:256
	s_nop 1
	v_fmamk_f32 v64, v171, 0x3a800000, v223
	v_rsq_f32_e32 v66, v64
	s_nop 0
	v_mul_f32_e32 v66, 0xbfb8aa3b, v66
	v_mad_i64_i32 v[64:65], s[0:1], v170, s89, v[156:157]
	v_lshl_add_u64 v[64:65], v[64:65], 0, v[158:159]
	v_fma_f32 v206, v60, v66, v214
	v_fma_f32 v207, v61, v66, v215
	v_fma_f32 v208, v62, v66, v216
	v_fma_f32 v209, v63, v66, v217
	v_fma_f32 v210, v56, v66, v218
	v_fma_f32 v211, v57, v66, v219
	v_fma_f32 v212, v58, v66, v220
	v_fma_f32 v213, v59, v66, v221
	v_exp_f32_e32 v206, v206
	v_exp_f32_e32 v207, v207
	v_exp_f32_e32 v208, v208
	v_exp_f32_e32 v209, v209
	v_exp_f32_e32 v210, v210
	v_exp_f32_e32 v211, v211
	v_exp_f32_e32 v212, v212
	v_exp_f32_e32 v213, v213
	v_add_f32_e32 v206, 1.0, v206
	v_add_f32_e32 v207, 1.0, v207
	v_add_f32_e32 v208, 1.0, v208
	v_add_f32_e32 v209, 1.0, v209
	v_add_f32_e32 v210, 1.0, v210
	v_add_f32_e32 v211, 1.0, v211
	v_add_f32_e32 v212, 1.0, v212
	v_add_f32_e32 v213, 1.0, v213
	v_rcp_f32_e32 v60, v206
	v_rcp_f32_e32 v61, v207
	v_rcp_f32_e32 v62, v208
	v_rcp_f32_e32 v63, v209
	v_rcp_f32_e32 v67, v210
	v_rcp_f32_e32 v68, v211
	v_rcp_f32_e32 v69, v212
	v_rcp_f32_e32 v59, v213
	v_cvt_pk_bf16_f32 v56, v60, v61
	v_cvt_pk_bf16_f32 v57, v62, v63
	v_cvt_pk_bf16_f32 v58, v67, v68
	v_cvt_pk_bf16_f32 v59, v69, v59
	global_store_dwordx4 v[64:65], v[56:59], off
	s_nop 1
	v_fma_f32 v206, v48, v66, v234
	v_fma_f32 v207, v49, v66, v235
	v_fma_f32 v208, v50, v66, v236
	v_fma_f32 v209, v51, v66, v237
	v_fma_f32 v210, v36, v66, v250
	v_fma_f32 v211, v37, v66, v251
	v_fma_f32 v212, v38, v66, v252
	v_fma_f32 v213, v39, v66, v253
	v_exp_f32_e32 v206, v206
	v_exp_f32_e32 v207, v207
	v_exp_f32_e32 v208, v208
	v_exp_f32_e32 v209, v209
	v_exp_f32_e32 v210, v210
	v_exp_f32_e32 v211, v211
	v_exp_f32_e32 v212, v212
	v_exp_f32_e32 v213, v213
	v_add_f32_e32 v206, 1.0, v206
	v_add_f32_e32 v207, 1.0, v207
	v_add_f32_e32 v208, 1.0, v208
	v_add_f32_e32 v209, 1.0, v209
	v_add_f32_e32 v210, 1.0, v210
	v_add_f32_e32 v211, 1.0, v211
	v_add_f32_e32 v212, 1.0, v212
	v_add_f32_e32 v213, 1.0, v213
	v_rcp_f32_e32 v48, v206
	v_rcp_f32_e32 v49, v207
	v_rcp_f32_e32 v50, v208
	v_rcp_f32_e32 v51, v209
	v_rcp_f32_e32 v56, v210
	v_rcp_f32_e32 v57, v211
	v_rcp_f32_e32 v58, v212
	v_rcp_f32_e32 v39, v213
; __device__ __forceinline__ u32x4 pack8(const float* f) { u32x4 w; w.x = cvt_pk_bf16(f[0], f[1]); w.y = cvt_pk_bf16(f[2], f[3]); w.z = cvt_pk_bf16(f[4], f[5]); w.w = cvt_pk_bf16(f[6], f[7]); return w; }
;     __device__ __forceinline__ void operator()(AccT& acc, const Unit& u, int wr, int wc, int fr, int fq) const {
;     ...
;         for (int ai = 0; ai < 2; ++ai)
; #pragma unroll
;             for (int m = 0; m < 4; ++m) {
;                 const int row = u.pm * 256 + ai * 128 + wr * 64 + m * 16 + fr;
;                 const float rs = __builtin_amdgcn_rsqf(rsv[ai][m] * (1.0f / 1024.0f) + EPS);
;                 bf16_t* rowp = P + (size_t)row * INW + col0;
; #pragma unroll
;                 for (int bj = 0; bj < 2; ++bj) {
;                     float v[8];
; #pragma unroll
;                     for (int n = 0; n < 2; ++n)
; #pragma unroll
;                         for (int j = 0; j < 4; ++j) {
;                             float x = acc[ai][bj][m][n][j] * rs;
;                             if (gate) { x += gb[bj][n][j]; x = __builtin_amdgcn_rcpf(1.0f + __builtin_amdgcn_exp2f(-LOG2E * x)); }
;                             v[n * 4 + j] = x;
;                         }
;                     *(u32x4*)(rowp + bj * 128) = pack8(v);
;                 }
	v_cvt_pk_bf16_f32 v36, v48, v49
	v_cvt_pk_bf16_f32 v37, v50, v51
	v_cvt_pk_bf16_f32 v38, v56, v57
	v_cvt_pk_bf16_f32 v39, v58, v39
	global_store_dwordx4 v[64:65], v[36:39], off offset:256
	s_nop 1
	v_fmamk_f32 v36, v169, 0x3a800000, v223
	v_rsq_f32_e32 v38, v36
	s_nop 0
	v_mul_f32_e32 v38, 0xbfb8aa3b, v38
	v_mad_i64_i32 v[36:37], s[0:1], v168, s89, v[156:157]
	v_lshl_add_u64 v[36:37], v[36:37], 0, v[158:159]
	v_fma_f32 v206, v28, v38, v214
	v_fma_f32 v207, v29, v38, v215
	v_fma_f32 v208, v30, v38, v216
	v_fma_f32 v209, v31, v38, v217
	v_fma_f32 v210, v24, v38, v218
	v_fma_f32 v211, v25, v38, v219
	v_fma_f32 v212, v26, v38, v220
	v_fma_f32 v213, v27, v38, v221
	v_exp_f32_e32 v206, v206
	v_exp_f32_e32 v207, v207
	v_exp_f32_e32 v208, v208
	v_exp_f32_e32 v209, v209
	v_exp_f32_e32 v210, v210
	v_exp_f32_e32 v211, v211
	v_exp_f32_e32 v212, v212
	v_exp_f32_e32 v213, v213
	v_add_f32_e32 v206, 1.0, v206
	v_add_f32_e32 v207, 1.0, v207
	v_add_f32_e32 v208, 1.0, v208
	v_add_f32_e32 v209, 1.0, v209
	v_add_f32_e32 v210, 1.0, v210
	v_add_f32_e32 v211, 1.0, v211
	v_add_f32_e32 v212, 1.0, v212
	v_add_f32_e32 v213, 1.0, v213
	v_rcp_f32_e32 v28, v206
	v_rcp_f32_e32 v29, v207
	v_rcp_f32_e32 v30, v208
	v_rcp_f32_e32 v31, v209
	v_rcp_f32_e32 v39, v210
	v_rcp_f32_e32 v48, v211
	v_rcp_f32_e32 v49, v212
	v_rcp_f32_e32 v27, v213
	v_cvt_pk_bf16_f32 v24, v28, v29
	v_cvt_pk_bf16_f32 v25, v30, v31
	v_cvt_pk_bf16_f32 v26, v39, v48
	v_cvt_pk_bf16_f32 v27, v49, v27
	global_store_dwordx4 v[36:37], v[24:27], off
	s_nop 1
	v_fma_f32 v206, v20, v38, v234
	v_fma_f32 v207, v21, v38, v235
	v_fma_f32 v208, v22, v38, v236
	v_fma_f32 v209, v23, v38, v237
	v_fma_f32 v210, v16, v38, v250
	v_fma_f32 v211, v17, v38, v251
	v_fma_f32 v212, v18, v38, v252
	v_fma_f32 v213, v19, v38, v253
	v_exp_f32_e32 v206, v206
	v_exp_f32_e32 v207, v207
	v_exp_f32_e32 v208, v208
	v_exp_f32_e32 v209, v209
	v_exp_f32_e32 v210, v210
	v_exp_f32_e32 v211, v211
	v_exp_f32_e32 v212, v212
	v_exp_f32_e32 v213, v213
	v_add_f32_e32 v206, 1.0, v206
	v_add_f32_e32 v207, 1.0, v207
	v_add_f32_e32 v208, 1.0, v208
	v_add_f32_e32 v209, 1.0, v209
	v_add_f32_e32 v210, 1.0, v210
	v_add_f32_e32 v211, 1.0, v211
	v_add_f32_e32 v212, 1.0, v212
	v_add_f32_e32 v213, 1.0, v213
	v_rcp_f32_e32 v20, v206
	v_rcp_f32_e32 v21, v207
	v_rcp_f32_e32 v22, v208
	v_rcp_f32_e32 v23, v209
	v_rcp_f32_e32 v24, v210
	v_rcp_f32_e32 v25, v211
	v_rcp_f32_e32 v26, v212
	v_rcp_f32_e32 v19, v213
	v_cvt_pk_bf16_f32 v16, v20, v21
	v_cvt_pk_bf16_f32 v17, v22, v23
	v_cvt_pk_bf16_f32 v18, v24, v25
	v_cvt_pk_bf16_f32 v19, v26, v19
	global_store_dwordx4 v[36:37], v[16:19], off offset:256
	s_nop 1
	v_fmamk_f32 v16, v167, 0x3a800000, v223
	v_rsq_f32_e32 v18, v16
	v_mad_i64_i32 v[16:17], s[0:1], v166, s89, v[156:157]
	v_lshl_add_u64 v[16:17], v[16:17], 0, v[158:159]
	v_fmac_f32_e32 v52, v12, v18
	v_mul_f32_e32 v19, v12, v18
	v_mul_f32_e32 v12, 0xbfb8aa3b, v52
	v_exp_f32_e32 v12, v12
	v_fmac_f32_e32 v53, v13, v18
	v_fmac_f32_e32 v54, v14, v18
	v_fmac_f32_e32 v55, v15, v18
	v_add_f32_e32 v12, 1.0, v12
	v_rcp_f32_e32 v12, v12
	v_fmac_f32_e32 v44, v8, v18
	v_fmac_f32_e32 v45, v9, v18
	v_fmac_f32_e32 v46, v10, v18
	v_cndmask_b32_e64 v12, v19, v12, s[42:43]
	v_mul_f32_e32 v19, v13, v18
	v_mul_f32_e32 v13, 0xbfb8aa3b, v53
	v_exp_f32_e32 v13, v13
	v_fmac_f32_e32 v47, v11, v18
	v_fmac_f32_e32 v40, v4, v18
	v_fmac_f32_e32 v41, v5, v18
	v_add_f32_e32 v13, 1.0, v13
	v_rcp_f32_e32 v13, v13
	v_fmac_f32_e32 v42, v6, v18
	v_fmac_f32_e32 v43, v7, v18
	v_fmac_f32_e32 v32, v0, v18
	v_cndmask_b32_e64 v13, v19, v13, s[42:43]
	v_mul_f32_e32 v19, v14, v18
	v_mul_f32_e32 v14, 0xbfb8aa3b, v54
	v_exp_f32_e32 v14, v14
	v_fmac_f32_e32 v33, v1, v18
	v_fmac_f32_e32 v34, v2, v18
	v_fmac_f32_e32 v35, v3, v18
	v_add_f32_e32 v14, 1.0, v14
	v_rcp_f32_e32 v14, v14
	s_mov_b64 s[0:1], -1
	v_cndmask_b32_e64 v14, v19, v14, s[42:43]
	v_mul_f32_e32 v19, v15, v18
	v_mul_f32_e32 v15, 0xbfb8aa3b, v55
	v_exp_f32_e32 v15, v15
	s_nop 0
	v_add_f32_e32 v15, 1.0, v15
	v_rcp_f32_e32 v15, v15
	s_nop 0
	v_cndmask_b32_e64 v15, v19, v15, s[42:43]
	v_mul_f32_e32 v19, v8, v18
	v_mul_f32_e32 v8, 0xbfb8aa3b, v44
	v_exp_f32_e32 v8, v8
	s_nop 0
	v_add_f32_e32 v8, 1.0, v8
	v_rcp_f32_e32 v8, v8
	s_nop 0
	v_cndmask_b32_e64 v19, v19, v8, s[42:43]
	v_mul_f32_e32 v8, v9, v18
	v_mul_f32_e32 v9, 0xbfb8aa3b, v45
	v_exp_f32_e32 v9, v9
	s_nop 0
	v_add_f32_e32 v9, 1.0, v9
	v_rcp_f32_e32 v9, v9
	s_nop 0
	v_cndmask_b32_e64 v20, v8, v9, s[42:43]
	v_mul_f32_e32 v9, 0xbfb8aa3b, v46
	v_exp_f32_e32 v9, v9
	v_mul_f32_e32 v8, v10, v18
	v_add_f32_e32 v9, 1.0, v9
	v_rcp_f32_e32 v9, v9
	s_nop 0
	v_cndmask_b32_e64 v21, v8, v9, s[42:43]
	v_mul_f32_e32 v9, 0xbfb8aa3b, v47
	v_exp_f32_e32 v9, v9
	v_mul_f32_e32 v8, v11, v18
	v_add_f32_e32 v9, 1.0, v9
	v_rcp_f32_e32 v9, v9
	s_nop 0
	v_cndmask_b32_e64 v11, v8, v9, s[42:43]
	v_cvt_pk_bf16_f32 v8, v12, v13
	v_cvt_pk_bf16_f32 v9, v14, v15
	v_cvt_pk_bf16_f32 v10, v19, v20
	v_cvt_pk_bf16_f32 v11, v21, v11
	global_store_dwordx4 v[16:17], v[8:11], off
	s_nop 1
	v_mul_f32_e32 v8, v4, v18
	v_mul_f32_e32 v4, 0xbfb8aa3b, v40
	v_exp_f32_e32 v4, v4
	s_nop 0
	v_add_f32_e32 v4, 1.0, v4
	v_rcp_f32_e32 v4, v4
	s_nop 0
	v_cndmask_b32_e64 v4, v8, v4, s[42:43]
	v_mul_f32_e32 v8, v5, v18
	v_mul_f32_e32 v5, 0xbfb8aa3b, v41
	v_exp_f32_e32 v5, v5
	s_nop 0
	v_add_f32_e32 v5, 1.0, v5
	v_rcp_f32_e32 v5, v5
	s_nop 0
	v_cndmask_b32_e64 v5, v8, v5, s[42:43]
	v_mul_f32_e32 v8, v6, v18
	v_mul_f32_e32 v6, 0xbfb8aa3b, v42
	v_exp_f32_e32 v6, v6
	s_nop 0
	v_add_f32_e32 v6, 1.0, v6
	v_rcp_f32_e32 v6, v6
	s_nop 0
	v_cndmask_b32_e64 v6, v8, v6, s[42:43]
	v_mul_f32_e32 v8, v7, v18
	v_mul_f32_e32 v7, 0xbfb8aa3b, v43
	v_exp_f32_e32 v7, v7
	s_nop 0
	v_add_f32_e32 v7, 1.0, v7
	v_rcp_f32_e32 v7, v7
	s_nop 0
	v_cndmask_b32_e64 v7, v8, v7, s[42:43]
	v_mul_f32_e32 v8, v0, v18
	v_mul_f32_e32 v0, 0xbfb8aa3b, v32
	v_exp_f32_e32 v0, v0
	s_nop 0
	v_add_f32_e32 v0, 1.0, v0
	v_rcp_f32_e32 v0, v0
	s_nop 0
	v_cndmask_b32_e64 v8, v8, v0, s[42:43]
	v_mul_f32_e32 v0, v1, v18
	v_mul_f32_e32 v1, 0xbfb8aa3b, v33
	v_exp_f32_e32 v1, v1
	s_nop 0
	v_add_f32_e32 v1, 1.0, v1
	v_rcp_f32_e32 v1, v1
	s_nop 0
	v_cndmask_b32_e64 v9, v0, v1, s[42:43]
	v_mul_f32_e32 v1, 0xbfb8aa3b, v34
	v_exp_f32_e32 v1, v1
	v_mul_f32_e32 v0, v2, v18
	v_add_f32_e32 v1, 1.0, v1
	v_rcp_f32_e32 v1, v1
	s_nop 0
	v_cndmask_b32_e64 v10, v0, v1, s[42:43]
	v_mul_f32_e32 v1, 0xbfb8aa3b, v35
	v_exp_f32_e32 v1, v1
	v_mul_f32_e32 v0, v3, v18
	v_add_f32_e32 v1, 1.0, v1
	v_rcp_f32_e32 v1, v1
	s_nop 0
	v_cndmask_b32_e64 v3, v0, v1, s[42:43]
	v_cvt_pk_bf16_f32 v0, v4, v5
	v_cvt_pk_bf16_f32 v1, v6, v7
	v_cvt_pk_bf16_f32 v2, v8, v9
	v_cvt_pk_bf16_f32 v3, v10, v3
	global_store_dwordx4 v[16:17], v[0:3], off offset:256
	s_branch .Lmy_p1_join
